# s2 + attention PV sections: block-level lgkmcnt(0) replaced by counted lgkmcnt(6/4/2/0) before each MFMA
# speedup vs baseline: 1.0062x; 1.0062x over previous
; #define SBAR() __builtin_amdgcn_sched_barrier(0)
; __device__ __forceinline__ void finishSM(f32x16& p0, f32x16& p1, float alpha, float& l_reg, bf16x8& pa0, bf16x8& pa1, bf16x8& pa2, bf16x8& pa3) {
;   for (int r = 0; r < 16; ++r) p1[r] = __builtin_amdgcn_exp2f(p1[r]);
;   float ps = 0; for (int r = 0; r < 16; ++r) ps += p0[r]; for (int r = 0; r < 16; ++r) ps += p1[r];
;   { auto rr = __builtin_amdgcn_permlane32_swap(__float_as_uint(ps), __float_as_uint(ps), false, false);
;     ps = __uint_as_float(rr[0]) + __uint_as_float(rr[1]); }
;   l_reg = l_reg * alpha + ps;
;     ...
;   PK4(p0, 0, pa0); PK4(p0, 8, pa1); PK4(p1, 0, pa2); PK4(p1, 8, pa3);
;     ...
; }
; __device__ __forceinline__ void qkt(f32x16& p0, f32x16& p1, const bf16* Ks, const bf16x8* qr, int r32, int hi) {
;   p0 = f32x16{}; p1 = f32x16{};
;   for (int d0 = 0; d0 < 8; ++d0) { int cb = (d0 * 16 + hi * 8) * 2;
;     bf16x8 b0 = *reinterpret_cast<const bf16x8*>((const char*)Ks + KSWZ(r32, cb));
;     bf16x8 b1 = *reinterpret_cast<const bf16x8*>((const char*)Ks + KSWZ(32 + r32, cb));
;     p0 = __builtin_amdgcn_mfma_f32_32x32x16_bf16(b0, qr[d0], p0, 0, 0, 0);
;     p1 = __builtin_amdgcn_mfma_f32_32x32x16_bf16(b1, qr[d0], p1, 0, 0, 0); }
; }
; __device__ __forceinline__ int v_st(int k, int c) { const int kk = (k & ~0xC) | ((k & 4) << 1) | ((k & 8) >> 1); return ((kk >> 3) * 4 + (c >> 5)) * 512 + ((kk & 7) * 32 + (c & 31)) * 2; }
; __device__ __forceinline__ int v_rd_base(int lane) { return ((lane & 3) << 3) | (((lane >> 2) & 3) << 6) | (((lane >> 4) & 1) << 5) | (((lane >> 5) & 1) << 8); }
; template <int OFF> __device__ __forceinline__ s16x4 tr_read(int vb) {
;   s16x4 r; asm volatile("ds_read_b64_tr_b16 %0, %1 offset:%2" : "=&v"(r) : "v"(vb), "i"(OFF) : "memory"); return r;
; }
; template <int D0> __device__ __forceinline__ void pv_one(f32x16& od, int vb, bf16x8 pa0, bf16x8 pa1, bf16x8 pa2, bf16x8 pa3) {
;   const s16x4 l0 = tr_read<v_rd_off(D0, 0, 0)>(vb), h0 = tr_read<v_rd_off(D0, 0, 1)>(vb), l1 = tr_read<v_rd_off(D0, 1, 0)>(vb), h1 = tr_read<v_rd_off(D0, 1, 1)>(vb);
;   const s16x4 l2 = tr_read<v_rd_off(D0, 2, 0)>(vb), h2 = tr_read<v_rd_off(D0, 2, 1)>(vb), l3 = tr_read<v_rd_off(D0, 3, 0)>(vb), h3 = tr_read<v_rd_off(D0, 3, 1)>(vb);
;   asm volatile("s_waitcnt lgkmcnt(0)" ::: "memory"); SBAR();
.LBB0_602:
	ds_read_b128 v[64:67], v192 offset:49152
	ds_read_b128 v[68:71], v192 offset:57344
	ds_read_b128 v[146:149], v201 offset:49152
	ds_read_b128 v[150:153], v201 offset:57344
	v_exp_f32_e32 v160, v162
	v_add_f32_e32 v162, 0, v223
	s_waitcnt lgkmcnt(3)
	v_mfma_f32_32x32x16_bf16 v[80:95], v[64:67], v[126:129], 0
	v_add_f32_e32 v162, v224, v162
	v_add_f32_e32 v162, v225, v162
	v_add_f32_e32 v162, v227, v162
	v_add_f32_e32 v162, v229, v162
	v_add_f32_e32 v162, v230, v162
	v_add_f32_e32 v162, v226, v162
	v_add_f32_e32 v162, v228, v162
	s_waitcnt lgkmcnt(2)
	v_mfma_f32_32x32x16_bf16 v[64:79], v[68:71], v[126:129], 0
	v_add_f32_e32 v162, v215, v162
	v_add_f32_e32 v162, v217, v162
	v_add_f32_e32 v162, v219, v162
	v_add_f32_e32 v162, v221, v162
	v_add_f32_e32 v162, v216, v162
	v_add_f32_e32 v162, v218, v162
	v_add_f32_e32 v162, v220, v162
	s_waitcnt lgkmcnt(1)
	v_mfma_f32_32x32x16_bf16 v[80:95], v[146:149], v[122:125], v[80:95]
	v_add_f32_e32 v162, v222, v162
	v_exp_f32_e32 v154, v164
	v_exp_f32_e32 v155, v165
	v_exp_f32_e32 v156, v172
	v_exp_f32_e32 v157, v173
	v_exp_f32_e32 v158, v168
	v_exp_f32_e32 v159, v169
	s_waitcnt lgkmcnt(0)
	v_mfma_f32_32x32x16_bf16 v[64:79], v[150:153], v[122:125], v[64:79]
	ds_read_b128 v[146:149], v200 offset:49152
	ds_read_b128 v[150:153], v200 offset:57344
	v_exp_f32_e32 v161, v163
	v_cvt_pk_bf16_f32 v164, v229, v230
	v_cvt_pk_bf16_f32 v163, v225, v227
	v_cvt_pk_bf16_f32 v165, v226, v228
	v_cvt_pk_bf16_f32 v168, v216, v218
	v_cvt_pk_bf16_f32 v169, v220, v222
	s_waitcnt lgkmcnt(1)
	v_mfma_f32_32x32x16_bf16 v[80:95], v[146:149], v[134:137], v[80:95]
	v_permlane32_swap_b32_e32 v163, v165
	s_waitcnt lgkmcnt(0)
	v_mfma_f32_32x32x16_bf16 v[64:79], v[150:153], v[134:137], v[64:79]
	ds_read_b128 v[146:149], v195 offset:49152
	ds_read_b128 v[150:153], v195 offset:57344
	s_waitcnt lgkmcnt(1)
	v_mfma_f32_32x32x16_bf16 v[80:95], v[146:149], v[130:133], v[80:95]
	s_waitcnt lgkmcnt(0)
	v_mfma_f32_32x32x16_bf16 v[64:79], v[150:153], v[130:133], v[64:79]
	ds_read_b128 v[146:149], v194 offset:49152
	ds_read_b128 v[150:153], v194 offset:57344
	s_waitcnt lgkmcnt(1)
	v_mfma_f32_32x32x16_bf16 v[80:95], v[146:149], v[118:121], v[80:95]
	s_waitcnt lgkmcnt(0)
	v_mfma_f32_32x32x16_bf16 v[64:79], v[150:153], v[118:121], v[64:79]
	ds_read_b128 v[146:149], v193 offset:49152
	ds_read_b128 v[150:153], v193 offset:57344
	s_waitcnt lgkmcnt(1)
	v_mfma_f32_32x32x16_bf16 v[80:95], v[146:149], v[114:117], v[80:95]
	s_waitcnt lgkmcnt(0)
	v_mfma_f32_32x32x16_bf16 v[64:79], v[150:153], v[114:117], v[64:79]
	ds_read_b128 v[146:149], v207 offset:49152
	ds_read_b128 v[150:153], v207 offset:57344
	s_waitcnt lgkmcnt(1)
	v_mfma_f32_32x32x16_bf16 v[80:95], v[146:149], v[110:113], v[80:95]
	s_waitcnt lgkmcnt(0)
	v_mfma_f32_32x32x16_bf16 v[64:79], v[150:153], v[110:113], v[64:79]
	ds_read_b128 v[146:149], v206 offset:49152
	ds_read_b128 v[150:153], v206 offset:57344
	s_waitcnt lgkmcnt(1)
	v_mfma_f32_32x32x16_bf16 v[80:95], v[146:149], v[106:109], v[80:95]
	v_exp_f32_e32 v146, v176
	v_exp_f32_e32 v147, v177
	v_exp_f32_e32 v148, v174
	v_exp_f32_e32 v149, v175
	v_add_f32_e32 v162, v146, v162
	v_add_f32_e32 v162, v147, v162
	v_add_f32_e32 v162, v148, v162
	s_waitcnt lgkmcnt(0)
	v_mfma_f32_32x32x16_bf16 v[64:79], v[150:153], v[106:109], v[64:79]
	v_exp_f32_e32 v150, v170
	v_exp_f32_e32 v151, v171
	v_exp_f32_e32 v152, v166
	v_exp_f32_e32 v153, v167
	v_add_f32_e32 v162, v149, v162
	v_add_f32_e32 v162, v150, v162
	v_add_f32_e32 v162, v151, v162
	v_add_f32_e32 v162, v152, v162
	v_add_f32_e32 v162, v153, v162
	v_add_f32_e32 v162, v154, v162
	v_add_f32_e32 v162, v155, v162
	v_add_f32_e32 v162, v156, v162
	v_add_f32_e32 v162, v157, v162
	v_add_f32_e32 v162, v158, v162
	v_add_f32_e32 v162, v159, v162
	v_add_f32_e32 v162, v160, v162
	v_add_f32_e32 v211, v161, v162
	v_mov_b32_e32 v212, v211
	v_cvt_pk_bf16_f32 v162, v223, v224
	s_nop 0
	v_permlane32_swap_b32_e32 v211, v212
	v_permlane32_swap_b32_e32 v162, v164
	v_cvt_pk_bf16_f32 v166, v215, v217
	v_cvt_pk_bf16_f32 v167, v219, v221
	v_cvt_pk_bf16_f32 v170, v146, v147
	v_cvt_pk_bf16_f32 v171, v148, v149
	v_cvt_pk_bf16_f32 v172, v150, v151
	v_cvt_pk_bf16_f32 v173, v152, v153
	v_cvt_pk_bf16_f32 v174, v154, v155
	v_cvt_pk_bf16_f32 v175, v156, v157
	v_cvt_pk_bf16_f32 v176, v158, v159
	v_cvt_pk_bf16_f32 v177, v160, v161
	v_permlane32_swap_b32_e32 v166, v168
	v_permlane32_swap_b32_e32 v167, v169
	v_permlane32_swap_b32_e32 v170, v172
	v_permlane32_swap_b32_e32 v171, v173
	v_permlane32_swap_b32_e32 v174, v176
	v_permlane32_swap_b32_e32 v175, v177
	v_add_co_u32_e32 v146, vcc, s69, v182
	s_mov_b32 s8, 0xffff0000
	s_nop 0
	v_addc_co_u32_e32 v147, vcc, -1, v183, vcc
	v_add_co_u32_e32 v150, vcc, s8, v182
	s_mov_b32 s8, 0xff6e8000
	s_nop 0
	v_addc_co_u32_e32 v151, vcc, -1, v183, vcc
	v_add_co_u32_e32 v154, vcc, s8, v182
	s_mov_b32 s8, 0xff6f0000
	s_nop 0
	v_addc_co_u32_e32 v155, vcc, -1, v183, vcc
	v_add_co_u32_e32 v158, vcc, s8, v182
	global_load_dwordx4 v[146:149], v[146:147], off
	s_nop 0
	global_load_dwordx4 v[150:153], v[150:151], off
	v_addc_co_u32_e32 v159, vcc, -1, v183, vcc
	global_load_dwordx4 v[154:157], v[154:155], off
	s_nop 0
	global_load_dwordx4 v[158:161], v[158:159], off
	ds_read_b64_tr_b16 v[214:215], v179 offset:0
	ds_read_b64_tr_b16 v[216:217], v179 offset:0x800
	ds_read_b64_tr_b16 v[218:219], v179 offset:0x1000
	ds_read_b64_tr_b16 v[220:221], v179 offset:0x1800
	ds_read_b64_tr_b16 v[222:223], v179 offset:0x2000
	ds_read_b64_tr_b16 v[224:225], v179 offset:0x2800
	ds_read_b64_tr_b16 v[226:227], v179 offset:0x3000
	ds_read_b64_tr_b16 v[228:229], v179 offset:0x3800
	s_waitcnt lgkmcnt(6)
; #define SBAR() __builtin_amdgcn_sched_barrier(0)
; template <int D0> __device__ __forceinline__ void pv_one(f32x16& od, int vb, bf16x8 pa0, bf16x8 pa1, bf16x8 pa2, bf16x8 pa3) {
;   const s16x4 l0 = tr_read<v_rd_off(D0, 0, 0)>(vb), h0 = tr_read<v_rd_off(D0, 0, 1)>(vb), l1 = tr_read<v_rd_off(D0, 1, 0)>(vb), h1 = tr_read<v_rd_off(D0, 1, 1)>(vb);
;   const s16x4 l2 = tr_read<v_rd_off(D0, 2, 0)>(vb), h2 = tr_read<v_rd_off(D0, 2, 1)>(vb), l3 = tr_read<v_rd_off(D0, 3, 0)>(vb), h3 = tr_read<v_rd_off(D0, 3, 1)>(vb);
;   asm volatile("s_waitcnt lgkmcnt(0)" ::: "memory"); SBAR();
;     ...
;   od = __builtin_amdgcn_mfma_f32_32x32x16_bf16(pa0, PK(l0, h0), od, 0, 0, 0);
;   od = __builtin_amdgcn_mfma_f32_32x32x16_bf16(pa1, PK(l1, h1), od, 0, 0, 0);
;   od = __builtin_amdgcn_mfma_f32_32x32x16_bf16(pa2, PK(l2, h2), od, 0, 0, 0);
;   od = __builtin_amdgcn_mfma_f32_32x32x16_bf16(pa3, PK(l3, h3), od, 0, 0, 0);
;     ...
; }
; __device__ __forceinline__ void pv_d0(f32x16* o, int vb, bf16x8 pa0, bf16x8 pa1, bf16x8 pa2, bf16x8 pa3) {
;   pv_one<0>(o[0], vb, pa0, pa1, pa2, pa3); pv_one<1>(o[1], vb, pa0, pa1, pa2, pa3); pv_one<2>(o[2], vb, pa0, pa1, pa2, pa3); pv_one<3>(o[3], vb, pa0, pa1, pa2, pa3);
; __device__ __forceinline__ void attn_dense_body(const bf16* __restrict__ Qb, const bf16* __restrict__ Kh, const bf16* __restrict__ Vh,
;                                                 const unsigned short* __restrict__ Gb, unsigned short* __restrict__ Yb, int seq, char* lds, const int tid) {
;     ...
;   f32x16 pA0, pA1, pB0, pB1; float mnA, mnB, alA, alB; bf16x8 pa0, pa1, pa2, pa3; const int NT = seq / KVBLK;
;   constexpr int SE = 0, SO = SDEPTH - 1;
;   SLOAD(SE, 0); asm volatile("s_waitcnt vmcnt(0)" ::: "memory"); SWRITE(0, SE); __syncthreads();
;   qkt(pA0, pA1, K_lds, qr, r32, hi); partialSM(pA0, pA1, m_reg, mnA, alA);
;   SLOAD(SO, KVBLK); if constexpr (SDEPTH == 2) { if (2 < NT) SLOAD(SE, 2 * KVBLK); }
;   SWAIT(); SWRITE(1, SO); __syncthreads();
;   for (int j = 1; j + 1 < NT; j += 2) {
;     SBAR(); qkt(pB0, pB1, (bf16*)((char*)K_lds + SHM_K), qr, r32, hi);
;     finishSM(pA0, pA1, alA, l_reg, pa0, pa1, pa2, pa3); SBAR();
;     SLOAD(SO, (j + SDEPTH) * KVBLK); SBAR();
;     pv_d0(o, vb0, pa0, pa1, pa2, pa3); partialSM(pB0, pB1, m_reg, mnB, alB);
;     __syncthreads(); SWAIT(); SWRITE(0, SE);
;     RESC(alB); __syncthreads();
	s_nop 0
	v_mfma_f32_32x32x16_bf16 v[0:15], v[162:165], v[214:217], v[0:15]
	ds_read_b64_tr_b16 v[214:215], v179 offset:0x200
	ds_read_b64_tr_b16 v[216:217], v179 offset:0xa00
	s_waitcnt lgkmcnt(6)
	v_mfma_f32_32x32x16_bf16 v[0:15], v[166:169], v[218:221], v[0:15]
	ds_read_b64_tr_b16 v[218:219], v179 offset:0x1200
	ds_read_b64_tr_b16 v[220:221], v179 offset:0x1a00
	s_waitcnt lgkmcnt(6)
	v_mfma_f32_32x32x16_bf16 v[0:15], v[170:173], v[222:225], v[0:15]
	ds_read_b64_tr_b16 v[222:223], v179 offset:0x2200
	ds_read_b64_tr_b16 v[224:225], v179 offset:0x2a00
	s_waitcnt lgkmcnt(6)
	v_mfma_f32_32x32x16_bf16 v[0:15], v[174:177], v[226:229], v[0:15]
	ds_read_b64_tr_b16 v[226:227], v179 offset:0x3200
	ds_read_b64_tr_b16 v[228:229], v179 offset:0x3a00
	s_waitcnt lgkmcnt(6)
	v_mfma_f32_32x32x16_bf16 v[48:63], v[162:165], v[214:217], v[48:63]
	ds_read_b64_tr_b16 v[214:215], v179 offset:0x400
	ds_read_b64_tr_b16 v[216:217], v179 offset:0xc00
	s_waitcnt lgkmcnt(6)
	v_mfma_f32_32x32x16_bf16 v[48:63], v[166:169], v[218:221], v[48:63]
	ds_read_b64_tr_b16 v[218:219], v179 offset:0x1400
	ds_read_b64_tr_b16 v[220:221], v179 offset:0x1c00
	s_waitcnt lgkmcnt(6)
	v_mfma_f32_32x32x16_bf16 v[48:63], v[170:173], v[222:225], v[48:63]
	ds_read_b64_tr_b16 v[222:223], v179 offset:0x2400
	ds_read_b64_tr_b16 v[224:225], v179 offset:0x2c00
	s_waitcnt lgkmcnt(6)
	v_mfma_f32_32x32x16_bf16 v[48:63], v[174:177], v[226:229], v[48:63]
	ds_read_b64_tr_b16 v[226:227], v179 offset:0x3400
	ds_read_b64_tr_b16 v[228:229], v179 offset:0x3c00
	s_waitcnt lgkmcnt(6)
	v_mfma_f32_32x32x16_bf16 v[32:47], v[162:165], v[214:217], v[32:47]
	ds_read_b64_tr_b16 v[214:215], v179 offset:0x600
	ds_read_b64_tr_b16 v[216:217], v179 offset:0xe00
	s_waitcnt lgkmcnt(6)
	v_mfma_f32_32x32x16_bf16 v[32:47], v[166:169], v[218:221], v[32:47]
	ds_read_b64_tr_b16 v[218:219], v179 offset:0x1600
	ds_read_b64_tr_b16 v[220:221], v179 offset:0x1e00
	s_waitcnt lgkmcnt(6)
	v_mfma_f32_32x32x16_bf16 v[32:47], v[170:173], v[222:225], v[32:47]
	ds_read_b64_tr_b16 v[222:223], v179 offset:0x2600
	ds_read_b64_tr_b16 v[224:225], v179 offset:0x2e00
	s_waitcnt lgkmcnt(6)
	v_mfma_f32_32x32x16_bf16 v[32:47], v[174:177], v[226:229], v[32:47]
	ds_read_b64_tr_b16 v[226:227], v179 offset:0x3600
	ds_read_b64_tr_b16 v[228:229], v179 offset:0x3e00
	s_waitcnt lgkmcnt(6)
	v_mfma_f32_32x32x16_bf16 v[16:31], v[162:165], v[214:217], v[16:31]
	v_max_f32_e32 v162, v81, v81
	v_max_f32_e32 v163, v80, v80
	v_max_f32_e32 v162, v163, v162
	v_max3_f32 v162, v162, v82, v83
	v_max3_f32 v162, v162, v84, v85
	v_max3_f32 v162, v162, v86, v87
	v_max3_f32 v162, v162, v88, v89
	v_max3_f32 v162, v162, v90, v91
	v_max3_f32 v162, v162, v92, v93
	s_waitcnt lgkmcnt(4)
	v_mfma_f32_32x32x16_bf16 v[16:31], v[166:169], v[218:221], v[16:31]
	v_max3_f32 v162, v162, v94, v95
	v_max3_f32 v162, v162, v64, v65
	v_max3_f32 v162, v162, v66, v67
	v_max3_f32 v162, v162, v68, v69
	v_max3_f32 v162, v162, v70, v71
	v_max3_f32 v162, v162, v72, v73
	v_max3_f32 v162, v162, v74, v75
	v_max3_f32 v162, v162, v76, v77
	s_waitcnt lgkmcnt(2)
	v_mfma_f32_32x32x16_bf16 v[16:31], v[170:173], v[222:225], v[16:31]
	v_max3_f32 v162, v162, v78, v79
	v_mov_b32_e32 v163, v162
	s_nop 1
	v_permlane32_swap_b32_e32 v162, v163
	v_max_f32_e32 v163, v163, v163
	v_max_f32_e32 v162, v162, v162
	v_max_f32_e32 v162, v162, v163
	v_sub_f32_e32 v163, v162, v210
	v_cmp_ge_f32_e32 vcc, s68, v163
	v_max_f32_e32 v163, v210, v210
	v_max_f32_e32 v162, v163, v162
	s_waitcnt lgkmcnt(0)
	v_mfma_f32_32x32x16_bf16 v[16:31], v[174:177], v[226:229], v[16:31]
	v_sub_f32_e32 v163, v210, v162
	v_mul_f32_e32 v163, 0x3e0293ee, v163
	v_exp_f32_e32 v163, v163
	s_cmp_eq_u64 vcc, exec
	s_cselect_b64 s[8:9], -1, 0
	s_barrier
	s_waitcnt vmcnt(4)
	v_cndmask_b32_e64 v214, v163, 1.0, s[8:9]
	v_cmp_gt_f32_e32 vcc, 1.0, v214
	s_waitcnt vmcnt(7)
	ds_write_b128 v204, v[98:101]
	s_waitcnt vmcnt(6)
	ds_write_b128 v205, v[138:141]
	s_waitcnt vmcnt(5)
	ds_write_b128 v202, v[102:105] offset:32768
	s_waitcnt vmcnt(4)
	ds_write_b128 v203, v[142:145] offset:32768
	s_cbranch_vccz .LBB0_606
	s_and_saveexec_b64 s[12:13], s[6:7]
	ds_write_b32 v189, v214 offset:128
	s_or_b64 exec, exec, s[12:13]
	s_waitcnt lgkmcnt(0)
	v_add_u32_e32 v163, v181, v180
	ds_read_b128 v[164:167], v163 offset:224
	ds_read_b128 v[168:171], v163 offset:192
	ds_read_b128 v[172:175], v163 offset:160
	ds_read_b128 v[216:219], v163 offset:128
	s_waitcnt lgkmcnt(3)
	v_pk_mul_f32 v[12:13], v[12:13], v[164:165]
	s_waitcnt lgkmcnt(2)
	v_pk_mul_f32 v[8:9], v[8:9], v[168:169]
	s_waitcnt lgkmcnt(1)
	v_pk_mul_f32 v[4:5], v[4:5], v[172:173]
	v_pk_mul_f32 v[14:15], v[14:15], v[166:167]
	v_pk_mul_f32 v[10:11], v[10:11], v[170:171]
	v_pk_mul_f32 v[6:7], v[6:7], v[174:175]
	s_waitcnt lgkmcnt(0)
	v_pk_mul_f32 v[2:3], v[2:3], v[218:219]
	v_pk_mul_f32 v[0:1], v[0:1], v[216:217]
	v_pk_mul_f32 v[60:61], v[60:61], v[164:165]
	v_pk_mul_f32 v[56:57], v[56:57], v[168:169]
	v_pk_mul_f32 v[52:53], v[52:53], v[172:173]
	v_pk_mul_f32 v[62:63], v[62:63], v[166:167]
	v_pk_mul_f32 v[58:59], v[58:59], v[170:171]
	v_pk_mul_f32 v[54:55], v[54:55], v[174:175]
	v_pk_mul_f32 v[50:51], v[50:51], v[218:219]
	v_pk_mul_f32 v[48:49], v[48:49], v[216:217]
	v_pk_mul_f32 v[44:45], v[44:45], v[164:165]
	v_pk_mul_f32 v[40:41], v[40:41], v[168:169]
	v_pk_mul_f32 v[36:37], v[36:37], v[172:173]
	v_pk_mul_f32 v[46:47], v[46:47], v[166:167]
	v_pk_mul_f32 v[42:43], v[42:43], v[170:171]
	v_pk_mul_f32 v[38:39], v[38:39], v[174:175]
	v_pk_mul_f32 v[34:35], v[34:35], v[218:219]
	v_pk_mul_f32 v[32:33], v[32:33], v[216:217]
	v_pk_mul_f32 v[28:29], v[28:29], v[164:165]
	v_pk_mul_f32 v[24:25], v[24:25], v[168:169]
	v_pk_mul_f32 v[20:21], v[20:21], v[172:173]
	v_pk_mul_f32 v[30:31], v[30:31], v[166:167]
	v_pk_mul_f32 v[26:27], v[26:27], v[170:171]
	v_pk_mul_f32 v[22:23], v[22:23], v[174:175]
	v_pk_mul_f32 v[18:19], v[18:19], v[218:219]
	v_pk_mul_f32 v[16:17], v[16:17], v[216:217]

; #define SBAR() __builtin_amdgcn_sched_barrier(0)
; #define SWAIT() do { if constexpr (SDEPTH == 2) asm volatile("s_waitcnt vmcnt(4)" ::: "memory"); else asm volatile("s_waitcnt vmcnt(0)" ::: "memory"); } while (0)
; #define RESC(a) do { if (__any((a) < 1.f)) { if (hi == 0) al_l[r32] = (a); asm volatile("s_waitcnt lgkmcnt(0)" ::: "memory"); \
;     for (int d = 0; d < 4; ++d) for (int r = 0; r < 16; ++r) o[d][r] *= al_l[crow(r, hi)]; } } while (0)
; template <int D0> __device__ __forceinline__ void pv_one(f32x16& od, int vb, bf16x8 pa0, bf16x8 pa1, bf16x8 pa2, bf16x8 pa3) {
;   const s16x4 l0 = tr_read<v_rd_off(D0, 0, 0)>(vb), h0 = tr_read<v_rd_off(D0, 0, 1)>(vb), l1 = tr_read<v_rd_off(D0, 1, 0)>(vb), h1 = tr_read<v_rd_off(D0, 1, 1)>(vb);
;   const s16x4 l2 = tr_read<v_rd_off(D0, 2, 0)>(vb), h2 = tr_read<v_rd_off(D0, 2, 1)>(vb), l3 = tr_read<v_rd_off(D0, 3, 0)>(vb), h3 = tr_read<v_rd_off(D0, 3, 1)>(vb);
;   asm volatile("s_waitcnt lgkmcnt(0)" ::: "memory"); SBAR();
;     ...
;   od = __builtin_amdgcn_mfma_f32_32x32x16_bf16(pa0, PK(l0, h0), od, 0, 0, 0);
;   od = __builtin_amdgcn_mfma_f32_32x32x16_bf16(pa1, PK(l1, h1), od, 0, 0, 0);
;   od = __builtin_amdgcn_mfma_f32_32x32x16_bf16(pa2, PK(l2, h2), od, 0, 0, 0);
;   od = __builtin_amdgcn_mfma_f32_32x32x16_bf16(pa3, PK(l3, h3), od, 0, 0, 0);
;     ...
; }
; __device__ __forceinline__ void pv_d0(f32x16* o, int vb, bf16x8 pa0, bf16x8 pa1, bf16x8 pa2, bf16x8 pa3) {
;   pv_one<0>(o[0], vb, pa0, pa1, pa2, pa3); pv_one<1>(o[1], vb, pa0, pa1, pa2, pa3); pv_one<2>(o[2], vb, pa0, pa1, pa2, pa3); pv_one<3>(o[3], vb, pa0, pa1, pa2, pa3);
; __device__ __forceinline__ void attn_dense_body(const bf16* __restrict__ Qb, const bf16* __restrict__ Kh, const bf16* __restrict__ Vh,
;                                                 const unsigned short* __restrict__ Gb, unsigned short* __restrict__ Yb, int seq, char* lds, const int tid) {
;     ...
;     pv_d0(o, vb0 + (int)SHM_V, pa0, pa1, pa2, pa3); partialSM(pA0, pA1, m_reg, mnA, alA);
;     __syncthreads(); SWAIT(); SWRITE(1, SO);
;     RESC(alA); __syncthreads();
.LBB0_608:
	ds_read_b64_tr_b16 v[216:217], v191 offset:0
	ds_read_b64_tr_b16 v[218:219], v191 offset:0x800
	ds_read_b64_tr_b16 v[220:221], v191 offset:0x1000
	ds_read_b64_tr_b16 v[222:223], v191 offset:0x1800
	ds_read_b64_tr_b16 v[224:225], v191 offset:0x2000
	ds_read_b64_tr_b16 v[226:227], v191 offset:0x2800
	ds_read_b64_tr_b16 v[242:243], v191 offset:0x3000
	ds_read_b64_tr_b16 v[244:245], v191 offset:0x3800
	s_waitcnt lgkmcnt(6)
	s_nop 0
	v_mfma_f32_32x32x16_bf16 v[0:15], v[162:165], v[216:219], v[0:15]
	ds_read_b64_tr_b16 v[216:217], v191 offset:0x200
	ds_read_b64_tr_b16 v[218:219], v191 offset:0xa00
	s_waitcnt lgkmcnt(6)
	v_mfma_f32_32x32x16_bf16 v[0:15], v[166:169], v[220:223], v[0:15]
	ds_read_b64_tr_b16 v[220:221], v191 offset:0x1200
	ds_read_b64_tr_b16 v[222:223], v191 offset:0x1a00
	s_waitcnt lgkmcnt(6)
	v_mfma_f32_32x32x16_bf16 v[0:15], v[170:173], v[224:227], v[0:15]
	ds_read_b64_tr_b16 v[224:225], v191 offset:0x2200
	ds_read_b64_tr_b16 v[226:227], v191 offset:0x2a00
	s_waitcnt lgkmcnt(6)
	v_mfma_f32_32x32x16_bf16 v[0:15], v[174:177], v[242:245], v[0:15]
	ds_read_b64_tr_b16 v[242:243], v191 offset:0x3200
	ds_read_b64_tr_b16 v[244:245], v191 offset:0x3a00
	s_waitcnt lgkmcnt(6)
	v_mfma_f32_32x32x16_bf16 v[48:63], v[162:165], v[216:219], v[48:63]
	ds_read_b64_tr_b16 v[216:217], v191 offset:0x400
	ds_read_b64_tr_b16 v[218:219], v191 offset:0xc00
	s_waitcnt lgkmcnt(6)
	v_mfma_f32_32x32x16_bf16 v[48:63], v[166:169], v[220:223], v[48:63]
	ds_read_b64_tr_b16 v[220:221], v191 offset:0x1400
	ds_read_b64_tr_b16 v[222:223], v191 offset:0x1c00
	s_waitcnt lgkmcnt(6)
	v_mfma_f32_32x32x16_bf16 v[48:63], v[170:173], v[224:227], v[48:63]
	ds_read_b64_tr_b16 v[224:225], v191 offset:0x2400
	ds_read_b64_tr_b16 v[226:227], v191 offset:0x2c00
	s_waitcnt lgkmcnt(6)
	v_mfma_f32_32x32x16_bf16 v[48:63], v[174:177], v[242:245], v[48:63]
	ds_read_b64_tr_b16 v[242:243], v191 offset:0x3400
	ds_read_b64_tr_b16 v[244:245], v191 offset:0x3c00
	s_waitcnt lgkmcnt(6)
	v_mfma_f32_32x32x16_bf16 v[32:47], v[162:165], v[216:219], v[32:47]
	ds_read_b64_tr_b16 v[216:217], v191 offset:0x600
	ds_read_b64_tr_b16 v[218:219], v191 offset:0xe00
	s_waitcnt lgkmcnt(6)
	v_mfma_f32_32x32x16_bf16 v[32:47], v[166:169], v[220:223], v[32:47]
	ds_read_b64_tr_b16 v[220:221], v191 offset:0x1600
	ds_read_b64_tr_b16 v[222:223], v191 offset:0x1e00
	s_waitcnt lgkmcnt(6)
	v_mfma_f32_32x32x16_bf16 v[32:47], v[170:173], v[224:227], v[32:47]
	ds_read_b64_tr_b16 v[224:225], v191 offset:0x2600
	ds_read_b64_tr_b16 v[226:227], v191 offset:0x2e00
	s_waitcnt lgkmcnt(6)
	v_mfma_f32_32x32x16_bf16 v[32:47], v[174:177], v[242:245], v[32:47]
	ds_read_b64_tr_b16 v[242:243], v191 offset:0x3600
	ds_read_b64_tr_b16 v[244:245], v191 offset:0x3e00
	s_waitcnt lgkmcnt(6)
	v_mfma_f32_32x32x16_bf16 v[16:31], v[162:165], v[216:219], v[16:31]
	v_max_f32_e32 v162, v81, v81
	v_max_f32_e32 v163, v80, v80
	v_max_f32_e32 v162, v163, v162
	v_max3_f32 v162, v162, v82, v83
	v_max3_f32 v162, v162, v84, v85
	v_max3_f32 v162, v162, v86, v87
	v_max3_f32 v162, v162, v88, v89
	v_max3_f32 v162, v162, v90, v91
	v_max3_f32 v162, v162, v92, v93
	s_waitcnt lgkmcnt(4)
	v_mfma_f32_32x32x16_bf16 v[16:31], v[166:169], v[220:223], v[16:31]
	v_max3_f32 v162, v162, v94, v95
	v_max3_f32 v162, v162, v64, v65
	v_max3_f32 v162, v162, v66, v67
	v_max3_f32 v162, v162, v68, v69
	v_max3_f32 v162, v162, v70, v71
	v_max3_f32 v162, v162, v72, v73
	v_max3_f32 v162, v162, v74, v75
	v_max3_f32 v162, v162, v76, v77
	s_waitcnt lgkmcnt(2)
	v_mfma_f32_32x32x16_bf16 v[16:31], v[170:173], v[224:227], v[16:31]
	v_max3_f32 v162, v162, v78, v79
	v_mov_b32_e32 v163, v162
	s_nop 1
	v_permlane32_swap_b32_e32 v162, v163
	v_max_f32_e32 v163, v163, v163
	v_max_f32_e32 v162, v162, v162
	v_max_f32_e32 v162, v162, v163
	v_sub_f32_e32 v163, v162, v210
	v_cmp_ge_f32_e32 vcc, s68, v163
	v_max_f32_e32 v163, v210, v210
	v_max_f32_e32 v162, v163, v162
	s_waitcnt lgkmcnt(0)
	v_mfma_f32_32x32x16_bf16 v[16:31], v[174:177], v[242:245], v[16:31]
	v_sub_f32_e32 v163, v210, v162
	v_mul_f32_e32 v163, 0x3e0293ee, v163
	v_exp_f32_e32 v163, v163
	s_cmp_eq_u64 vcc, exec
	s_cselect_b64 s[8:9], -1, 0
	s_barrier
	s_waitcnt vmcnt(4)
	v_cndmask_b32_e64 v213, v163, 1.0, s[8:9]
	v_cmp_gt_f32_e32 vcc, 1.0, v213
	s_waitcnt vmcnt(3)
	ds_write_b128 v204, v[146:149] offset:16384
	s_waitcnt vmcnt(2)
	ds_write_b128 v205, v[150:153] offset:16384
	s_waitcnt vmcnt(1)
	ds_write_b128 v202, v[154:157] offset:49152
	s_waitcnt vmcnt(0)
	ds_write_b128 v203, v[158:161] offset:49152
	s_cbranch_vccz .LBB0_612
	s_and_saveexec_b64 s[18:19], s[6:7]
	ds_write_b32 v189, v213 offset:128
	s_or_b64 exec, exec, s[18:19]
	s_waitcnt lgkmcnt(0)
	v_add_u32_e32 v158, v181, v180
	ds_read_b128 v[146:149], v158 offset:224
	ds_read_b128 v[150:153], v158 offset:192
	ds_read_b128 v[154:157], v158 offset:160
	ds_read_b128 v[158:161], v158 offset:128
	s_waitcnt lgkmcnt(3)
	v_pk_mul_f32 v[12:13], v[12:13], v[146:147]
	s_waitcnt lgkmcnt(2)
	v_pk_mul_f32 v[8:9], v[8:9], v[150:151]
	s_waitcnt lgkmcnt(1)
	v_pk_mul_f32 v[4:5], v[4:5], v[154:155]
	v_pk_mul_f32 v[14:15], v[14:15], v[148:149]
	v_pk_mul_f32 v[10:11], v[10:11], v[152:153]
	v_pk_mul_f32 v[6:7], v[6:7], v[156:157]
	s_waitcnt lgkmcnt(0)
	v_pk_mul_f32 v[2:3], v[2:3], v[160:161]
	v_pk_mul_f32 v[0:1], v[0:1], v[158:159]
	v_pk_mul_f32 v[60:61], v[60:61], v[146:147]
	v_pk_mul_f32 v[56:57], v[56:57], v[150:151]
	v_pk_mul_f32 v[52:53], v[52:53], v[154:155]
	v_pk_mul_f32 v[62:63], v[62:63], v[148:149]
	v_pk_mul_f32 v[58:59], v[58:59], v[152:153]
	v_pk_mul_f32 v[54:55], v[54:55], v[156:157]
	v_pk_mul_f32 v[50:51], v[50:51], v[160:161]
	v_pk_mul_f32 v[48:49], v[48:49], v[158:159]
	v_pk_mul_f32 v[44:45], v[44:45], v[146:147]
	v_pk_mul_f32 v[40:41], v[40:41], v[150:151]
	v_pk_mul_f32 v[36:37], v[36:37], v[154:155]
	v_pk_mul_f32 v[46:47], v[46:47], v[148:149]
	v_pk_mul_f32 v[42:43], v[42:43], v[152:153]
	v_pk_mul_f32 v[38:39], v[38:39], v[156:157]
	v_pk_mul_f32 v[34:35], v[34:35], v[160:161]
	v_pk_mul_f32 v[32:33], v[32:33], v[158:159]
	v_pk_mul_f32 v[28:29], v[28:29], v[146:147]
	v_pk_mul_f32 v[24:25], v[24:25], v[150:151]
	v_pk_mul_f32 v[20:21], v[20:21], v[154:155]
	v_pk_mul_f32 v[30:31], v[30:31], v[148:149]
	v_pk_mul_f32 v[26:27], v[26:27], v[152:153]
	v_pk_mul_f32 v[22:23], v[22:23], v[156:157]
	v_pk_mul_f32 v[18:19], v[18:19], v[160:161]
	v_pk_mul_f32 v[16:17], v[16:17], v[158:159]

; #define SBAR() __builtin_amdgcn_sched_barrier(0)
; __device__ __forceinline__ void attn_dense_body(const bf16* __restrict__ Qb, const bf16* __restrict__ Kh, const bf16* __restrict__ Vh,
;                                                 const unsigned short* __restrict__ Gb, unsigned short* __restrict__ Yb, int seq, char* lds, const int tid) {
;     ...
;   const unsigned short* Gw = Gb + (long)(wid * QBLK) * LDG;
;   const int rsub = lane >> 4, c8 = (lane & 15) * 8;
;   u32x4 gv[8];
; #pragma unroll
;   for (int it = 0; it < 8; ++it) gv[it] = *reinterpret_cast<const u32x4*>(Gw + (long)(it * 4 + rsub) * LDG + c8);
;   SBAR(); qkt(pB0, pB1, (bf16*)((char*)K_lds + SHM_K), qr, r32, hi);
;   finishSM(pA0, pA1, alA, l_reg, pa0, pa1, pa2, pa3); SBAR();
;   pv_d0(o, vb0, pa0, pa1, pa2, pa3); partialSM(pB0, pB1, m_reg, mnB, alB);
.LBB0_614:
	s_mul_i32 s9, s14, 0xc000
	s_mul_hi_i32 s8, s14, 0xc000
	s_add_u32 s9, s4, s9
	s_addc_u32 s8, s5, s8
	s_lshl_b32 s16, s47, 1
	s_add_u32 s9, s9, s16
	s_addc_u32 s12, s8, 0
	s_add_u32 s8, s9, 0x26401800
	s_addc_u32 s9, s12, 0
	v_mov_b64_e32 v[64:65], s[8:9]
	v_lshrrev_b32_e32 v182, 4, v208
	v_mad_i64_i32 v[64:65], s[8:9], v178, s64, v[64:65]
	v_lshlrev_b32_e32 v96, 1, v96
	v_mul_u32_u24_e32 v66, 0x6000, v182
	v_lshl_add_u64 v[64:65], v[64:65], 0, v[96:97]
	v_lshlrev_b32_e32 v66, 1, v66
	v_mov_b32_e32 v67, v97
	v_lshl_add_u64 v[68:69], v[64:65], 0, v[66:67]
	v_add_co_u32_e32 v70, vcc, s92, v68
	s_nop 1
	v_addc_co_u32_e32 v71, vcc, 0, v69, vcc
	global_load_dwordx4 v[158:161], v[68:69], off
	global_load_dwordx4 v[154:157], v[70:71], off
	v_add_co_u32_e32 v70, vcc, s94, v68
	s_nop 1
	v_addc_co_u32_e32 v71, vcc, 0, v69, vcc
	v_add_co_u32_e32 v68, vcc, s95, v68
	s_nop 1
	v_addc_co_u32_e32 v69, vcc, 0, v69, vcc
	global_load_dwordx4 v[150:153], v[70:71], off
	global_load_dwordx4 v[146:149], v[68:69], off
	v_or_b32_e32 v68, 0xc0000, v66
	v_mov_b32_e32 v69, v97
	v_lshl_add_u64 v[68:69], v[64:65], 0, v[68:69]
	v_add_u32_e32 v70, 0xf0000, v66
	v_mov_b32_e32 v71, v97
	v_lshl_add_u64 v[70:71], v[64:65], 0, v[70:71]
	global_load_dwordx4 v[142:145], v[68:69], off
	global_load_dwordx4 v[138:141], v[70:71], off
	v_add_u32_e32 v68, 0x120000, v66
	v_mov_b32_e32 v69, v97
	v_lshl_add_u64 v[68:69], v[64:65], 0, v[68:69]
	v_add_u32_e32 v66, 0x150000, v66
	v_lshl_add_u64 v[64:65], v[64:65], 0, v[66:67]
	global_load_dwordx4 v[102:105], v[68:69], off
	global_load_dwordx4 v[98:101], v[64:65], off
	ds_read_b128 v[64:67], v192 offset:49152
	ds_read_b128 v[68:71], v192 offset:57344
	s_waitcnt lgkmcnt(1)
	v_mfma_f32_32x32x16_bf16 v[80:95], v[64:67], v[126:129], 0
	s_waitcnt lgkmcnt(0)
	v_mfma_f32_32x32x16_bf16 v[64:79], v[68:71], v[126:129], 0
	ds_read_b128 v[126:129], v201 offset:49152
	ds_read_b128 v[202:205], v201 offset:57344
	s_waitcnt lgkmcnt(1)
	v_mfma_f32_32x32x16_bf16 v[80:95], v[126:129], v[122:125], v[80:95]
	s_waitcnt lgkmcnt(0)
	v_mfma_f32_32x32x16_bf16 v[64:79], v[202:205], v[122:125], v[64:79]
	ds_read_b128 v[122:125], v200 offset:49152
	ds_read_b128 v[126:129], v200 offset:57344
	s_waitcnt lgkmcnt(1)
	v_mfma_f32_32x32x16_bf16 v[80:95], v[122:125], v[134:137], v[80:95]
	s_waitcnt lgkmcnt(0)
	v_mfma_f32_32x32x16_bf16 v[64:79], v[126:129], v[134:137], v[64:79]
	ds_read_b128 v[122:125], v195 offset:49152
	ds_read_b128 v[126:129], v195 offset:57344
	s_waitcnt lgkmcnt(1)
	v_mfma_f32_32x32x16_bf16 v[80:95], v[122:125], v[130:133], v[80:95]
	s_waitcnt lgkmcnt(0)
	v_mfma_f32_32x32x16_bf16 v[64:79], v[126:129], v[130:133], v[64:79]
	ds_read_b128 v[122:125], v194 offset:49152
	ds_read_b128 v[126:129], v194 offset:57344
	v_exp_f32_e32 v130, v162
	v_exp_f32_e32 v131, v163
	s_waitcnt lgkmcnt(1)
	v_mfma_f32_32x32x16_bf16 v[80:95], v[122:125], v[118:121], v[80:95]
	s_waitcnt lgkmcnt(0)
	v_mfma_f32_32x32x16_bf16 v[64:79], v[126:129], v[118:121], v[64:79]
	ds_read_b128 v[118:121], v193 offset:49152
	ds_read_b128 v[122:125], v193 offset:57344
	v_exp_f32_e32 v126, v172
	v_exp_f32_e32 v127, v173
	v_exp_f32_e32 v128, v168
	v_exp_f32_e32 v129, v169
	s_waitcnt lgkmcnt(1)
	v_mfma_f32_32x32x16_bf16 v[80:95], v[118:121], v[114:117], v[80:95]
	s_waitcnt lgkmcnt(0)
	v_mfma_f32_32x32x16_bf16 v[64:79], v[122:125], v[114:117], v[64:79]
	ds_read_b128 v[114:117], v207 offset:49152
	ds_read_b128 v[118:121], v207 offset:57344
	v_exp_f32_e32 v122, v166
	v_exp_f32_e32 v123, v167
	v_exp_f32_e32 v124, v164
	v_exp_f32_e32 v125, v165
	s_waitcnt lgkmcnt(1)
	v_mfma_f32_32x32x16_bf16 v[80:95], v[114:117], v[110:113], v[80:95]
	s_waitcnt lgkmcnt(0)
	v_mfma_f32_32x32x16_bf16 v[64:79], v[118:121], v[110:113], v[64:79]
	ds_read_b128 v[110:113], v206 offset:49152
	ds_read_b128 v[114:117], v206 offset:57344
	v_exp_f32_e32 v118, v174
	v_exp_f32_e32 v119, v175
	v_exp_f32_e32 v120, v170
	v_exp_f32_e32 v121, v171
	s_waitcnt lgkmcnt(1)
	v_mfma_f32_32x32x16_bf16 v[80:95], v[110:113], v[106:109], v[80:95]
	v_cvt_pk_bf16_f32 v110, v229, v230
	v_cvt_pk_bf16_f32 v111, v226, v228
	v_cvt_pk_bf16_f32 v112, v215, v217
	v_cvt_pk_bf16_f32 v113, v219, v221
	s_waitcnt lgkmcnt(0)
	v_mfma_f32_32x32x16_bf16 v[64:79], v[114:117], v[106:109], v[64:79]
	v_add_f32_e32 v106, 0, v223
	v_add_f32_e32 v106, v224, v106
	v_add_f32_e32 v106, v225, v106
	v_add_f32_e32 v106, v227, v106
	v_add_f32_e32 v106, v229, v106
	v_add_f32_e32 v106, v230, v106
	v_add_f32_e32 v106, v226, v106
	v_add_f32_e32 v106, v228, v106
	v_add_f32_e32 v106, v215, v106
	v_add_f32_e32 v106, v217, v106
	v_add_f32_e32 v106, v219, v106
	v_add_f32_e32 v106, v221, v106
	v_exp_f32_e32 v116, v176
	v_add_f32_e32 v106, v216, v106
	v_exp_f32_e32 v117, v177
	v_add_f32_e32 v106, v218, v106
	v_add_f32_e32 v106, v220, v106
	v_add_f32_e32 v106, v222, v106
	v_add_f32_e32 v106, v116, v106
	v_add_f32_e32 v106, v117, v106
	v_add_f32_e32 v106, v118, v106
	v_add_f32_e32 v106, v119, v106
	v_add_f32_e32 v106, v120, v106
	v_add_f32_e32 v106, v121, v106
	v_add_f32_e32 v106, v122, v106
	v_add_f32_e32 v106, v123, v106
	v_add_f32_e32 v106, v124, v106
	v_add_f32_e32 v106, v125, v106
	v_add_f32_e32 v106, v126, v106
	v_add_f32_e32 v106, v127, v106
	v_add_f32_e32 v106, v128, v106
	v_add_f32_e32 v106, v129, v106
	v_add_f32_e32 v106, v130, v106
	v_add_f32_e32 v106, v131, v106
	v_mov_b32_e32 v107, v106
	v_cvt_pk_bf16_f32 v108, v223, v224
	v_cvt_pk_bf16_f32 v109, v225, v227
	v_permlane32_swap_b32_e32 v106, v107
	v_permlane32_swap_b32_e32 v108, v110
	v_permlane32_swap_b32_e32 v109, v111
	v_cvt_pk_bf16_f32 v114, v216, v218
	v_cvt_pk_bf16_f32 v115, v220, v222
	v_cvt_pk_bf16_f32 v116, v116, v117
	v_cvt_pk_bf16_f32 v117, v118, v119
	v_cvt_pk_bf16_f32 v118, v120, v121
	v_cvt_pk_bf16_f32 v119, v122, v123
	v_cvt_pk_bf16_f32 v120, v124, v125
	v_cvt_pk_bf16_f32 v121, v126, v127
	v_cvt_pk_bf16_f32 v122, v128, v129
	v_cvt_pk_bf16_f32 v123, v130, v131
	v_permlane32_swap_b32_e32 v112, v114
	v_permlane32_swap_b32_e32 v113, v115
	v_permlane32_swap_b32_e32 v116, v118
	v_permlane32_swap_b32_e32 v117, v119
	v_permlane32_swap_b32_e32 v120, v122
	v_permlane32_swap_b32_e32 v121, v123
	ds_read_b64_tr_b16 v[124:125], v179 offset:0
	ds_read_b64_tr_b16 v[126:127], v179 offset:0x800
	ds_read_b64_tr_b16 v[128:129], v179 offset:0x1000
	ds_read_b64_tr_b16 v[130:131], v179 offset:0x1800
	ds_read_b64_tr_b16 v[132:133], v179 offset:0x2000
	ds_read_b64_tr_b16 v[134:135], v179 offset:0x2800
	ds_read_b64_tr_b16 v[162:163], v179 offset:0x3000
	ds_read_b64_tr_b16 v[164:165], v179 offset:0x3800
	s_waitcnt lgkmcnt(6)
; #define SBAR() __builtin_amdgcn_sched_barrier(0)
; #define RESC(a) do { if (__any((a) < 1.f)) { if (hi == 0) al_l[r32] = (a); asm volatile("s_waitcnt lgkmcnt(0)" ::: "memory"); \
;     for (int d = 0; d < 4; ++d) for (int r = 0; r < 16; ++r) o[d][r] *= al_l[crow(r, hi)]; } } while (0)
; template <int D0> __device__ __forceinline__ void pv_one(f32x16& od, int vb, bf16x8 pa0, bf16x8 pa1, bf16x8 pa2, bf16x8 pa3) {
;   const s16x4 l0 = tr_read<v_rd_off(D0, 0, 0)>(vb), h0 = tr_read<v_rd_off(D0, 0, 1)>(vb), l1 = tr_read<v_rd_off(D0, 1, 0)>(vb), h1 = tr_read<v_rd_off(D0, 1, 1)>(vb);
;   const s16x4 l2 = tr_read<v_rd_off(D0, 2, 0)>(vb), h2 = tr_read<v_rd_off(D0, 2, 1)>(vb), l3 = tr_read<v_rd_off(D0, 3, 0)>(vb), h3 = tr_read<v_rd_off(D0, 3, 1)>(vb);
;   asm volatile("s_waitcnt lgkmcnt(0)" ::: "memory"); SBAR();
;     ...
;   od = __builtin_amdgcn_mfma_f32_32x32x16_bf16(pa0, PK(l0, h0), od, 0, 0, 0);
;   od = __builtin_amdgcn_mfma_f32_32x32x16_bf16(pa1, PK(l1, h1), od, 0, 0, 0);
;   od = __builtin_amdgcn_mfma_f32_32x32x16_bf16(pa2, PK(l2, h2), od, 0, 0, 0);
;   od = __builtin_amdgcn_mfma_f32_32x32x16_bf16(pa3, PK(l3, h3), od, 0, 0, 0);
;     ...
; }
; __device__ __forceinline__ void pv_d0(f32x16* o, int vb, bf16x8 pa0, bf16x8 pa1, bf16x8 pa2, bf16x8 pa3) {
;   pv_one<0>(o[0], vb, pa0, pa1, pa2, pa3); pv_one<1>(o[1], vb, pa0, pa1, pa2, pa3); pv_one<2>(o[2], vb, pa0, pa1, pa2, pa3); pv_one<3>(o[3], vb, pa0, pa1, pa2, pa3);
; __device__ __forceinline__ void attn_dense_body(const bf16* __restrict__ Qb, const bf16* __restrict__ Kh, const bf16* __restrict__ Vh,
;                                                 const unsigned short* __restrict__ Gb, unsigned short* __restrict__ Yb, int seq, char* lds, const int tid) {
;     ...
;   pv_d0(o, vb0, pa0, pa1, pa2, pa3); partialSM(pB0, pB1, m_reg, mnB, alB);
;   __syncthreads(); RESC(alB);
	s_nop 0
	v_mfma_f32_32x32x16_bf16 v[0:15], v[108:111], v[124:127], v[0:15]
	ds_read_b64_tr_b16 v[124:125], v179 offset:0x200
	ds_read_b64_tr_b16 v[126:127], v179 offset:0xa00
	s_waitcnt lgkmcnt(6)
	v_mfma_f32_32x32x16_bf16 v[0:15], v[112:115], v[128:131], v[0:15]
	ds_read_b64_tr_b16 v[128:129], v179 offset:0x1200
	ds_read_b64_tr_b16 v[130:131], v179 offset:0x1a00
	s_waitcnt lgkmcnt(6)
	v_mfma_f32_32x32x16_bf16 v[0:15], v[116:119], v[132:135], v[0:15]
	ds_read_b64_tr_b16 v[132:133], v179 offset:0x2200
	ds_read_b64_tr_b16 v[134:135], v179 offset:0x2a00
	s_waitcnt lgkmcnt(6)
	v_mfma_f32_32x32x16_bf16 v[0:15], v[120:123], v[162:165], v[0:15]
	ds_read_b64_tr_b16 v[162:163], v179 offset:0x3200
	ds_read_b64_tr_b16 v[164:165], v179 offset:0x3a00
	s_waitcnt lgkmcnt(6)
	v_mfma_f32_32x32x16_bf16 v[48:63], v[108:111], v[124:127], v[48:63]
	ds_read_b64_tr_b16 v[124:125], v179 offset:0x400
	ds_read_b64_tr_b16 v[126:127], v179 offset:0xc00
	s_waitcnt lgkmcnt(6)
	v_mfma_f32_32x32x16_bf16 v[48:63], v[112:115], v[128:131], v[48:63]
	ds_read_b64_tr_b16 v[128:129], v179 offset:0x1400
	ds_read_b64_tr_b16 v[130:131], v179 offset:0x1c00
	s_waitcnt lgkmcnt(6)
	v_mfma_f32_32x32x16_bf16 v[48:63], v[116:119], v[132:135], v[48:63]
	ds_read_b64_tr_b16 v[132:133], v179 offset:0x2400
	ds_read_b64_tr_b16 v[134:135], v179 offset:0x2c00
	s_waitcnt lgkmcnt(6)
	v_mfma_f32_32x32x16_bf16 v[48:63], v[120:123], v[162:165], v[48:63]
	ds_read_b64_tr_b16 v[162:163], v179 offset:0x3400
	ds_read_b64_tr_b16 v[164:165], v179 offset:0x3c00
	s_waitcnt lgkmcnt(6)
	v_mfma_f32_32x32x16_bf16 v[32:47], v[108:111], v[124:127], v[32:47]
	ds_read_b64_tr_b16 v[124:125], v179 offset:0x600
	ds_read_b64_tr_b16 v[126:127], v179 offset:0xe00
	s_waitcnt lgkmcnt(6)
	v_mfma_f32_32x32x16_bf16 v[32:47], v[112:115], v[128:131], v[32:47]
	ds_read_b64_tr_b16 v[128:129], v179 offset:0x1600
	ds_read_b64_tr_b16 v[130:131], v179 offset:0x1e00
	s_waitcnt lgkmcnt(6)
	v_mfma_f32_32x32x16_bf16 v[32:47], v[116:119], v[132:135], v[32:47]
	ds_read_b64_tr_b16 v[132:133], v179 offset:0x2600
	ds_read_b64_tr_b16 v[134:135], v179 offset:0x2e00
	s_waitcnt lgkmcnt(6)
	v_mfma_f32_32x32x16_bf16 v[32:47], v[120:123], v[162:165], v[32:47]
	ds_read_b64_tr_b16 v[162:163], v179 offset:0x3600
	ds_read_b64_tr_b16 v[164:165], v179 offset:0x3e00
	s_waitcnt lgkmcnt(6)
	v_mfma_f32_32x32x16_bf16 v[16:31], v[108:111], v[124:127], v[16:31]
	v_max_f32_e32 v108, v81, v81
	v_max_f32_e32 v109, v80, v80
	v_max_f32_e32 v108, v109, v108
	v_max3_f32 v108, v108, v82, v83
	v_max3_f32 v108, v108, v84, v85
	v_max3_f32 v108, v108, v86, v87
	v_max3_f32 v108, v108, v88, v89
	v_max3_f32 v108, v108, v90, v91
	v_max3_f32 v108, v108, v92, v93
	s_waitcnt lgkmcnt(4)
	v_mfma_f32_32x32x16_bf16 v[16:31], v[112:115], v[128:131], v[16:31]
	v_max3_f32 v108, v108, v94, v95
	v_max3_f32 v108, v108, v64, v65
	v_max3_f32 v108, v108, v66, v67
	v_max3_f32 v108, v108, v68, v69
	v_max3_f32 v108, v108, v70, v71
	v_max3_f32 v108, v108, v72, v73
	v_max3_f32 v108, v108, v74, v75
	v_max3_f32 v108, v108, v76, v77
	s_waitcnt lgkmcnt(2)
	v_mfma_f32_32x32x16_bf16 v[16:31], v[116:119], v[132:135], v[16:31]
	v_max3_f32 v108, v108, v78, v79
	v_mov_b32_e32 v109, v108
	s_nop 1
	v_permlane32_swap_b32_e32 v108, v109
	v_max_f32_e32 v109, v109, v109
	v_max_f32_e32 v108, v108, v108
	v_max_f32_e32 v108, v108, v109
	v_sub_f32_e32 v109, v108, v210
	v_cmp_ge_f32_e32 vcc, s68, v109
	v_max_f32_e32 v109, v210, v210
	v_max_f32_e32 v109, v109, v108
	s_waitcnt lgkmcnt(0)
	v_mfma_f32_32x32x16_bf16 v[16:31], v[120:123], v[162:165], v[16:31]
	v_sub_f32_e32 v108, v210, v109
	v_mul_f32_e32 v108, 0x3e0293ee, v108
	v_exp_f32_e32 v108, v108
	s_cmp_eq_u64 vcc, exec
	s_cselect_b64 s[8:9], -1, 0
	v_cndmask_b32_e64 v108, v108, 1.0, s[8:9]
	v_cmp_gt_f32_e32 vcc, 1.0, v108
	s_barrier
	s_cbranch_vccz .LBB0_618
	s_and_saveexec_b64 s[12:13], s[6:7]
	ds_write_b32 v189, v108 offset:128
	s_or_b64 exec, exec, s[12:13]
	s_waitcnt lgkmcnt(0)
	v_add_u32_e32 v122, v181, v180
	ds_read_b128 v[110:113], v122 offset:224
	ds_read_b128 v[114:117], v122 offset:192
	ds_read_b128 v[118:121], v122 offset:160
	ds_read_b128 v[122:125], v122 offset:128
	s_waitcnt lgkmcnt(3)
	v_pk_mul_f32 v[12:13], v[12:13], v[110:111]
	s_waitcnt lgkmcnt(2)
	v_pk_mul_f32 v[8:9], v[8:9], v[114:115]
	s_waitcnt lgkmcnt(1)
	v_pk_mul_f32 v[4:5], v[4:5], v[118:119]
	v_pk_mul_f32 v[14:15], v[14:15], v[112:113]
	v_pk_mul_f32 v[10:11], v[10:11], v[116:117]
	v_pk_mul_f32 v[6:7], v[6:7], v[120:121]
	s_waitcnt lgkmcnt(0)
	v_pk_mul_f32 v[2:3], v[2:3], v[124:125]
	v_pk_mul_f32 v[0:1], v[0:1], v[122:123]
	v_pk_mul_f32 v[60:61], v[60:61], v[110:111]
	v_pk_mul_f32 v[56:57], v[56:57], v[114:115]
	v_pk_mul_f32 v[52:53], v[52:53], v[118:119]
	v_pk_mul_f32 v[62:63], v[62:63], v[112:113]
	v_pk_mul_f32 v[58:59], v[58:59], v[116:117]
	v_pk_mul_f32 v[54:55], v[54:55], v[120:121]
	v_pk_mul_f32 v[50:51], v[50:51], v[124:125]
	v_pk_mul_f32 v[48:49], v[48:49], v[122:123]
	v_pk_mul_f32 v[44:45], v[44:45], v[110:111]
	v_pk_mul_f32 v[40:41], v[40:41], v[114:115]
	v_pk_mul_f32 v[36:37], v[36:37], v[118:119]
	v_pk_mul_f32 v[46:47], v[46:47], v[112:113]
	v_pk_mul_f32 v[42:43], v[42:43], v[116:117]
	v_pk_mul_f32 v[38:39], v[38:39], v[120:121]
	v_pk_mul_f32 v[34:35], v[34:35], v[124:125]
	v_pk_mul_f32 v[32:33], v[32:33], v[122:123]
	v_pk_mul_f32 v[28:29], v[28:29], v[110:111]
	v_pk_mul_f32 v[24:25], v[24:25], v[114:115]
	v_pk_mul_f32 v[20:21], v[20:21], v[118:119]
	v_pk_mul_f32 v[30:31], v[30:31], v[112:113]
	v_pk_mul_f32 v[26:27], v[26:27], v[116:117]
	v_pk_mul_f32 v[22:23], v[22:23], v[120:121]
	v_pk_mul_f32 v[18:19], v[18:19], v[124:125]
	v_pk_mul_f32 v[16:17], v[16:17], v[122:123]
; __device__ __forceinline__ void partialSM(f32x16& p0, f32x16& p1, float& m_reg, float& mn, float& alpha) {
;     ...
;   float mnC = -mn * C;
;   for (int r = 0; r < 16; ++r) p0[r] = fmaf(p0[r], C, mnC); for (int r = 0; r < 16; ++r) p1[r] = fmaf(p1[r], C, mnC);
;   for (int r = 0; r < 16; ++r) p0[r] = __builtin_amdgcn_exp2f(p0[r]);
; }
; __device__ __forceinline__ void finishSM(f32x16& p0, f32x16& p1, float alpha, float& l_reg, bf16x8& pa0, bf16x8& pa1, bf16x8& pa2, bf16x8& pa3) {
;   for (int r = 0; r < 16; ++r) p1[r] = __builtin_amdgcn_exp2f(p1[r]);
;   float ps = 0; for (int r = 0; r < 16; ++r) ps += p0[r]; for (int r = 0; r < 16; ++r) ps += p1[r];
;   { auto rr = __builtin_amdgcn_permlane32_swap(__float_as_uint(ps), __float_as_uint(ps), false, false);
;     ps = __uint_as_float(rr[0]) + __uint_as_float(rr[1]); }
;   l_reg = l_reg * alpha + ps;
;     ...
;   PK4(p0, 0, pa0); PK4(p0, 8, pa1); PK4(p1, 0, pa2); PK4(p1, 8, pa3);
;     ...
; }
.LBB0_618:
	v_cndmask_b32_e64 v109, v109, v210, s[8:9]
	v_mul_f32_e32 v109, 0xbe0293ee, v109
	v_fmamk_f32 v80, v80, 0x3e0293ee, v109
	v_fmamk_f32 v81, v81, 0x3e0293ee, v109
	v_fmamk_f32 v118, v93, 0x3e0293ee, v109
	v_fmamk_f32 v93, v74, 0x3e0293ee, v109
	v_exp_f32_e32 v74, v80
	v_fmamk_f32 v82, v82, 0x3e0293ee, v109
	v_fmamk_f32 v119, v94, 0x3e0293ee, v109
	v_fmamk_f32 v94, v75, 0x3e0293ee, v109
	v_exp_f32_e32 v75, v81
	v_fmamk_f32 v83, v83, 0x3e0293ee, v109
	v_fmamk_f32 v120, v95, 0x3e0293ee, v109
	v_fmamk_f32 v95, v76, 0x3e0293ee, v109
	v_exp_f32_e32 v76, v82
	v_fmamk_f32 v84, v84, 0x3e0293ee, v109
	v_fmamk_f32 v64, v64, 0x3e0293ee, v109
	v_exp_f32_e32 v80, v83
	v_fmamk_f32 v110, v85, 0x3e0293ee, v109
	v_fmamk_f32 v111, v86, 0x3e0293ee, v109
	v_fmamk_f32 v112, v87, 0x3e0293ee, v109
	v_fmamk_f32 v113, v88, 0x3e0293ee, v109
	v_fmamk_f32 v114, v89, 0x3e0293ee, v109
	v_fmamk_f32 v115, v90, 0x3e0293ee, v109
	v_fmamk_f32 v116, v91, 0x3e0293ee, v109
	v_fmamk_f32 v117, v92, 0x3e0293ee, v109
	v_fmamk_f32 v65, v65, 0x3e0293ee, v109
	v_fmamk_f32 v85, v66, 0x3e0293ee, v109
	v_fmamk_f32 v86, v67, 0x3e0293ee, v109
	v_fmamk_f32 v87, v68, 0x3e0293ee, v109
	v_fmamk_f32 v88, v69, 0x3e0293ee, v109
	v_fmamk_f32 v89, v70, 0x3e0293ee, v109
	v_fmamk_f32 v90, v71, 0x3e0293ee, v109
	v_fmamk_f32 v91, v72, 0x3e0293ee, v109
	v_fmamk_f32 v92, v73, 0x3e0293ee, v109
	v_exp_f32_e32 v81, v84
	v_fmamk_f32 v77, v77, 0x3e0293ee, v109
	v_fmamk_f32 v78, v78, 0x3e0293ee, v109
	v_fmac_f32_e32 v109, 0x3e0293ee, v79
	v_exp_f32_e32 v79, v64
	v_add_f32_e32 v64, 0, v74
	v_exp_f32_e32 v82, v110
	v_add_f32_e32 v64, v75, v64
	v_exp_f32_e32 v83, v111
	v_add_f32_e32 v64, v76, v64
	v_exp_f32_e32 v84, v112
	v_add_f32_e32 v64, v80, v64
	v_exp_f32_e32 v66, v113
	v_add_f32_e32 v64, v81, v64
	v_exp_f32_e32 v67, v114
	v_add_f32_e32 v64, v82, v64
	v_exp_f32_e32 v68, v115
	v_add_f32_e32 v64, v83, v64
	v_exp_f32_e32 v69, v116
	v_add_f32_e32 v64, v84, v64
	v_exp_f32_e32 v70, v117
	v_add_f32_e32 v64, v66, v64
	v_exp_f32_e32 v71, v118
	v_add_f32_e32 v64, v67, v64
	v_exp_f32_e32 v72, v119
	v_add_f32_e32 v64, v68, v64
	v_exp_f32_e32 v73, v120
	v_add_f32_e32 v64, v69, v64
	v_add_f32_e32 v64, v70, v64
	v_exp_f32_e32 v110, v65
	v_add_f32_e32 v64, v71, v64
	v_exp_f32_e32 v85, v85
	v_add_f32_e32 v64, v72, v64
	v_exp_f32_e32 v86, v86
	v_add_f32_e32 v64, v73, v64
	v_exp_f32_e32 v87, v87
	v_add_f32_e32 v64, v79, v64
	v_exp_f32_e32 v88, v88
	v_add_f32_e32 v64, v110, v64
	v_exp_f32_e32 v89, v89
	v_add_f32_e32 v64, v85, v64
	v_exp_f32_e32 v90, v90
	v_add_f32_e32 v64, v86, v64
	v_exp_f32_e32 v91, v91
	v_add_f32_e32 v64, v87, v64
	v_exp_f32_e32 v92, v92
	v_add_f32_e32 v64, v88, v64
	v_exp_f32_e32 v93, v93
	v_add_f32_e32 v64, v89, v64
	v_exp_f32_e32 v94, v94
	v_add_f32_e32 v64, v90, v64
	v_exp_f32_e32 v95, v95
	v_add_f32_e32 v64, v91, v64
	v_exp_f32_e32 v111, v77
	v_add_f32_e32 v64, v92, v64
	v_exp_f32_e32 v112, v78
	v_add_f32_e32 v64, v93, v64
	v_exp_f32_e32 v109, v109
	v_add_f32_e32 v64, v94, v64
	v_add_f32_e32 v64, v95, v64
	v_add_f32_e32 v64, v111, v64
	v_add_f32_e32 v64, v112, v64
	v_add_f32_e32 v64, v109, v64
	v_mov_b32_e32 v65, v64
	v_ashrrev_i32_e32 v179, 31, v178
	s_nop 0
	v_permlane32_swap_b32_e32 v64, v65
	v_cvt_pk_bf16_f32 v74, v74, v75
	v_cvt_pk_bf16_f32 v75, v76, v80
	v_cvt_pk_bf16_f32 v76, v81, v82
	v_cvt_pk_bf16_f32 v77, v83, v84
	v_cvt_pk_bf16_f32 v66, v66, v67
	v_cvt_pk_bf16_f32 v67, v68, v69
	v_cvt_pk_bf16_f32 v68, v70, v71
	v_cvt_pk_bf16_f32 v69, v72, v73
	v_cvt_pk_bf16_f32 v70, v79, v110
	v_cvt_pk_bf16_f32 v71, v85, v86
	v_cvt_pk_bf16_f32 v72, v87, v88
	v_cvt_pk_bf16_f32 v73, v89, v90
	v_cvt_pk_bf16_f32 v78, v91, v92
	v_cvt_pk_bf16_f32 v79, v93, v94
	v_cvt_pk_bf16_f32 v80, v95, v111
	v_cvt_pk_bf16_f32 v81, v112, v109
	v_permlane32_swap_b32_e32 v74, v76
	v_permlane32_swap_b32_e32 v75, v77
	v_permlane32_swap_b32_e32 v66, v68
	v_permlane32_swap_b32_e32 v67, v69
	v_permlane32_swap_b32_e32 v70, v72
	v_permlane32_swap_b32_e32 v71, v73
	v_permlane32_swap_b32_e32 v78, v80
	v_permlane32_swap_b32_e32 v79, v81
	ds_read_b64_tr_b16 v[82:83], v191 offset:0
	ds_read_b64_tr_b16 v[84:85], v191 offset:0x800
	ds_read_b64_tr_b16 v[86:87], v191 offset:0x1000
	ds_read_b64_tr_b16 v[88:89], v191 offset:0x1800
	ds_read_b64_tr_b16 v[90:91], v191 offset:0x2000
	ds_read_b64_tr_b16 v[92:93], v191 offset:0x2800
	ds_read_b64_tr_b16 v[110:111], v191 offset:0x3000
	ds_read_b64_tr_b16 v[112:113], v191 offset:0x3800
	s_waitcnt lgkmcnt(6)
; #define SBAR() __builtin_amdgcn_sched_barrier(0)
; template <int D0> __device__ __forceinline__ void pv_one(f32x16& od, int vb, bf16x8 pa0, bf16x8 pa1, bf16x8 pa2, bf16x8 pa3) {
;   const s16x4 l0 = tr_read<v_rd_off(D0, 0, 0)>(vb), h0 = tr_read<v_rd_off(D0, 0, 1)>(vb), l1 = tr_read<v_rd_off(D0, 1, 0)>(vb), h1 = tr_read<v_rd_off(D0, 1, 1)>(vb);
;   const s16x4 l2 = tr_read<v_rd_off(D0, 2, 0)>(vb), h2 = tr_read<v_rd_off(D0, 2, 1)>(vb), l3 = tr_read<v_rd_off(D0, 3, 0)>(vb), h3 = tr_read<v_rd_off(D0, 3, 1)>(vb);
;   asm volatile("s_waitcnt lgkmcnt(0)" ::: "memory"); SBAR();
;     ...
;   od = __builtin_amdgcn_mfma_f32_32x32x16_bf16(pa0, PK(l0, h0), od, 0, 0, 0);
;   od = __builtin_amdgcn_mfma_f32_32x32x16_bf16(pa1, PK(l1, h1), od, 0, 0, 0);
;   od = __builtin_amdgcn_mfma_f32_32x32x16_bf16(pa2, PK(l2, h2), od, 0, 0, 0);
;   od = __builtin_amdgcn_mfma_f32_32x32x16_bf16(pa3, PK(l3, h3), od, 0, 0, 0);
; __device__ __forceinline__ void attn_dense_body(const bf16* __restrict__ Qb, const bf16* __restrict__ Kh, const bf16* __restrict__ Vh,
;                                                 const unsigned short* __restrict__ Gb, unsigned short* __restrict__ Yb, int seq, char* lds, const int tid) {
;     ...
;   pv_d0(o, vb0 + (int)SHM_V, pa0, pa1, pa2, pa3);
;   if (hi == 0) li_l[r32] = l_reg; asm volatile("s_waitcnt lgkmcnt(0)" ::: "memory");
	s_nop 0
	v_mfma_f32_32x32x16_bf16 v[0:15], v[74:77], v[82:85], v[0:15]
	ds_read_b64_tr_b16 v[82:83], v191 offset:0x200
	ds_read_b64_tr_b16 v[84:85], v191 offset:0xa00
	s_waitcnt lgkmcnt(6)
	v_mfma_f32_32x32x16_bf16 v[0:15], v[66:69], v[86:89], v[0:15]
	ds_read_b64_tr_b16 v[86:87], v191 offset:0x1200
	ds_read_b64_tr_b16 v[88:89], v191 offset:0x1a00
	s_waitcnt lgkmcnt(6)
	v_mfma_f32_32x32x16_bf16 v[0:15], v[70:73], v[90:93], v[0:15]
	ds_read_b64_tr_b16 v[90:91], v191 offset:0x2200
	ds_read_b64_tr_b16 v[92:93], v191 offset:0x2a00
	s_waitcnt lgkmcnt(6)
	v_mfma_f32_32x32x16_bf16 v[0:15], v[78:81], v[110:113], v[0:15]
	ds_read_b64_tr_b16 v[110:111], v191 offset:0x3200
	ds_read_b64_tr_b16 v[112:113], v191 offset:0x3a00
	s_waitcnt lgkmcnt(6)
	v_mfma_f32_32x32x16_bf16 v[48:63], v[74:77], v[82:85], v[48:63]
	ds_read_b64_tr_b16 v[82:83], v191 offset:0x400
	ds_read_b64_tr_b16 v[84:85], v191 offset:0xc00
	s_waitcnt lgkmcnt(6)
	v_mfma_f32_32x32x16_bf16 v[48:63], v[66:69], v[86:89], v[48:63]
	ds_read_b64_tr_b16 v[86:87], v191 offset:0x1400
	ds_read_b64_tr_b16 v[88:89], v191 offset:0x1c00
	s_waitcnt lgkmcnt(6)
	v_mfma_f32_32x32x16_bf16 v[48:63], v[70:73], v[90:93], v[48:63]
	ds_read_b64_tr_b16 v[90:91], v191 offset:0x2400
	ds_read_b64_tr_b16 v[92:93], v191 offset:0x2c00
	s_waitcnt lgkmcnt(6)
	v_mfma_f32_32x32x16_bf16 v[48:63], v[78:81], v[110:113], v[48:63]
	ds_read_b64_tr_b16 v[110:111], v191 offset:0x3400
	ds_read_b64_tr_b16 v[112:113], v191 offset:0x3c00
	s_waitcnt lgkmcnt(6)
	v_mfma_f32_32x32x16_bf16 v[32:47], v[74:77], v[82:85], v[32:47]
	ds_read_b64_tr_b16 v[82:83], v191 offset:0x600
	ds_read_b64_tr_b16 v[84:85], v191 offset:0xe00
	s_waitcnt lgkmcnt(6)
	v_mfma_f32_32x32x16_bf16 v[32:47], v[66:69], v[86:89], v[32:47]
	ds_read_b64_tr_b16 v[86:87], v191 offset:0x1600
	ds_read_b64_tr_b16 v[88:89], v191 offset:0x1e00
	s_waitcnt lgkmcnt(6)
	v_mfma_f32_32x32x16_bf16 v[32:47], v[70:73], v[90:93], v[32:47]
	ds_read_b64_tr_b16 v[90:91], v191 offset:0x2600
	ds_read_b64_tr_b16 v[92:93], v191 offset:0x2e00
	s_waitcnt lgkmcnt(6)
	v_mfma_f32_32x32x16_bf16 v[32:47], v[78:81], v[110:113], v[32:47]
	ds_read_b64_tr_b16 v[110:111], v191 offset:0x3600
	ds_read_b64_tr_b16 v[112:113], v191 offset:0x3e00
	s_waitcnt lgkmcnt(6)
	v_mfma_f32_32x32x16_bf16 v[16:31], v[74:77], v[82:85], v[16:31]
	s_waitcnt lgkmcnt(4)
	v_mfma_f32_32x32x16_bf16 v[16:31], v[66:69], v[86:89], v[16:31]
	s_waitcnt lgkmcnt(2)
	v_mfma_f32_32x32x16_bf16 v[16:31], v[70:73], v[90:93], v[16:31]
	s_waitcnt lgkmcnt(0)
	v_mfma_f32_32x32x16_bf16 v[16:31], v[78:81], v[110:113], v[16:31]
	s_and_saveexec_b64 s[8:9], s[6:7]
	s_cbranch_execz .LBB0_596
	v_add_f32_e32 v66, v106, v107
	v_fmac_f32_e32 v66, v190, v213
	v_add_f32_e32 v64, v64, v65
	v_fmac_f32_e32 v64, v66, v108
	ds_write_b32 v189, v64
	s_branch .LBB0_596
